# XCD groups fully asynchronous after phase 1: group barriers + neighbour-group dependency waits replace grid barriers
# speedup vs baseline: 1.0126x; 1.0072x over previous
; __global__ void __launch_bounds__(NTHR, 2) mega(Params p, int ph_lo, int ph_hi) {
;     ...
;   cg::grid_group grid = cg::this_grid();
;   for (int ph = ph_lo; ph < ph_hi; ++ph) {
;     if (ph > ph_lo) grid.sync();
;     run_phase(p, ph, smem);
.LBB0_3:
	s_cmp_le_i32 s4, s30
	s_mov_b32 s12, 0x3a800000
	v_writelane_b32 v255, s4, 45
	s_cbranch_scc1 .LBB0_15
	s_sub_i32 s0, s4, s30
	s_cmp_lt_i32 s0, 2
	s_cbranch_scc1 .Lcg_sync
	s_waitcnt vmcnt(0) lgkmcnt(0)
	s_barrier
	s_mov_b64 s[0:1], exec
	v_readlane_b32 s6, v253, 4
	v_readlane_b32 s7, v253, 5
	s_and_b64 s[6:7], s[0:1], s[6:7]
	s_mov_b64 exec, s[6:7]
	s_cbranch_execz .Lfb_done
	buffer_wbl2 sc1
	s_sub_i32 s8, s4, s30
	v_readlane_b32 s9, v255, 13
	s_mov_b32 s10, 0x1fffc
	s_lshr_b32 s10, s10, s8
	s_and_b32 s11, s10, 1
	s_cmp_lt_i32 s8, 10
	s_cbranch_scc0 .Lfb_usey
	s_cmp_eq_u32 s11, 0
	s_cbranch_scc0 .Lfb_xl
	v_readlane_b32 s8, v255, 61
	s_add_i32 s8, s8, 1
	s_mov_b32 s10, 0x1cc2000
	v_writelane_b32 v255, s8, 61
	s_branch .Lfb_go

; __global__ void __launch_bounds__(NTHR, 2) mega(Params p, int ph_lo, int ph_hi) {
;     ...
;   for (int ph = ph_lo; ph < ph_hi; ++ph) {
;     if (ph > ph_lo) grid.sync();
;     run_phase(p, ph, smem);
.Lfb_rel:
	v_readlane_b32 s8, v255, 45
	s_sub_i32 s8, s8, s30
	v_readlane_b32 s9, v255, 9
	s_and_b32 s9, s9, 7
	s_mov_b32 s10, 0
	s_mov_b32 s11, 0x1cc2000
	s_movk_i32 s6, 0x60
	s_cmp_eq_u32 s8, 6
	s_cbranch_scc1 .Lnw_gu
	s_cmp_eq_u32 s8, 14
	s_cbranch_scc1 .Lnw_gu14
	s_movk_i32 s6, 0xe0
	s_cmp_eq_u32 s8, 9
	s_cbranch_scc1 .Lnw_k9
	s_cmp_eq_u32 s8, 10
	s_cbranch_scc1 .Lnw_k10
	s_branch .Lnw_done
.Lnw_gu14:
	s_mov_b32 s11, 0x4e2000
.Lnw_gu:
	s_add_i32 s7, s9, 1
	s_mov_b32 s10, 1
	s_cmp_lt_u32 s9, 7
	s_cbranch_scc1 .Lnw_loop
	s_mov_b32 s7, 0
	s_mov_b32 s10, 7
	s_branch .Lnw_loop
.Lnw_k9:
	s_cmp_eq_u32 s9, 0
	s_cbranch_scc1 .Lnw_done
	s_add_i32 s7, s9, -1
	s_mov_b32 s10, 1
	s_branch .Lnw_loop
.Lnw_k10:
	s_cmp_eq_u32 s9, 7
	s_cbranch_scc1 .Lnw_done
	s_mov_b32 s7, 7
	s_mov_b32 s10, 1
.Lnw_loop:
	s_lshl_b32 s4, s7, 8
	s_add_i32 s4, s4, s11
	s_addk_i32 s4, 0x100
	s_add_u32 s4, s88, s4
	s_addc_u32 s5, s89, 0
	s_movk_i32 s8, 0x4000
.Lnw_poll:
	global_load_dword v2, v1, s[4:5] sc1
	s_waitcnt vmcnt(0)
	v_cmp_gt_u32_e32 vcc, s6, v2
	s_cbranch_vccz .Lnw_next
	s_sleep 1
	s_add_i32 s8, s8, -1
	s_cmp_lg_u32 s8, 0
	s_cbranch_scc1 .Lnw_poll
.Lnw_next:
	s_add_i32 s7, s7, 1
	s_add_i32 s10, s10, -1
	s_cmp_lg_u32 s10, 0
	s_cbranch_scc1 .Lnw_loop

; DI void run_phase(const Params& p, int ph, char* smem) {
;     ...
;   const int layer = (ph - 1) >> 3, sub = (ph - 1) & 7;
;   const u16* wl = wtb + (size_t)layer * WT_LAYER;
;   switch (sub) {
;     case 0:
;       gemm8_phase<EPI_PROJ>(p, layer, actb, wl + WT_IN, 1024, 10, smem);
.LBB0_15:
	s_cmp_lg_u32 s4, 1
	s_cbranch_scc1 .Lstg_done
	s_and_b32 s6, s28, 7
	s_mulk_i32 s6, 16
	s_cmp_eq_u32 s6, 0
	s_cbranch_scc1 .Lstg_done
